# attention loop back-edge rotation (stage rotation before the per-tile barrier, exit path own barrier copy) + l-update and K/V pointer increments moved from the pre-barrier tail into the P.V section
# baseline (speedup 1.0000x reference)
; #define MFMA32(a, b, c) __builtin_amdgcn_mfma_f32_32x32x16_bf16((a), (b), (c), 0, 0, 0)
; DI void a_finishSM(f32x16& p0, f32x16& p1, float alpha, float& l_reg, bf16x8& pa0, bf16x8& pa1, bf16x8& pa2, bf16x8& pa3) {
; #pragma unroll
;   for (int r = 0; r < 16; ++r) p1[r] = __builtin_amdgcn_exp2f(p1[r]);
;   float ps = 0;
; #pragma unroll
;   for (int r = 0; r < 16; ++r) ps += p0[r];
; #pragma unroll
;   for (int r = 0; r < 16; ++r) ps += p1[r];
;   { auto rr = __builtin_amdgcn_permlane32_swap(__float_as_uint(ps), __float_as_uint(ps), false, false);
;     ps = __uint_as_float(rr[0]) + __uint_as_float(rr[1]); }
;   l_reg = l_reg * alpha + ps;
;     ...
;   PK4(p0, 0, pa0); PK4(p0, 8, pa1); PK4(p1, 0, pa2); PK4(p1, 8, pa3);
;     ...
; }
; DI void a_qkt(f32x16& p0, f32x16& p1, const char* Ks, const char* Ps, const bf16x8* qr, const char* QP, int r32, int hi) {
;   p0 = f32x16{}; p1 = f32x16{};
; #pragma unroll
;   for (int d0 = 0; d0 < 8; ++d0) { const int cb = (d0 * 16 + hi * 8) * 2;
;     bf16x8 b0 = *reinterpret_cast<const bf16x8*>(Ks + KSWZ(r32, cb));
;     bf16x8 b1 = *reinterpret_cast<const bf16x8*>(Ks + KSWZ(32 + r32, cb));
;     p0 = MFMA32(b0, qr[d0], p0);
;     p1 = MFMA32(b1, qr[d0], p1); }
; #pragma unroll
;   for (int d0 = 0; d0 < 4; ++d0) { const int cb = (d0 * 16 + hi * 8) * 2;
;     bf16x8 b0 = *reinterpret_cast<const bf16x8*>(Ps + PSWZ(r32, cb));
;     bf16x8 b1 = *reinterpret_cast<const bf16x8*>(Ps + PSWZ(32 + r32, cb));
;     const bf16x8 qp = *reinterpret_cast<const bf16x8*>(QP + d0 * 1024);
;     p0 = MFMA32(b0, qp, p0);
;     p1 = MFMA32(b1, qp, p1); }
.LBB0_669:
	s_waitcnt lgkmcnt(0)
	s_barrier
	v_add_u32_e32 v70, s9, v170
	ds_read_b128 v[66:69], v70 offset:16384
	ds_read_b128 v[70:73], v70 offset:24576
	v_add_u32_e32 v226, s9, v172
	ds_read_b128 v[204:207], v226 offset:16384
	ds_read_b128 v[208:211], v226 offset:24576
	v_sub_f32_e32 v144, v82, v153
	v_sub_f32_e32 v188, v83, v153
	v_sub_f32_e32 v189, v84, v153
	v_sub_f32_e32 v190, v85, v153
	v_sub_f32_e32 v191, v86, v153
	v_sub_f32_e32 v192, v87, v153
	v_sub_f32_e32 v193, v88, v153
	v_sub_f32_e32 v194, v89, v153
	v_sub_f32_e32 v195, v90, v153
	v_sub_f32_e32 v196, v91, v153
	v_sub_f32_e32 v197, v92, v153
	v_sub_f32_e32 v198, v93, v153
	v_sub_f32_e32 v199, v94, v153
	v_sub_f32_e32 v200, v95, v153
	v_sub_f32_e32 v201, v96, v153
	v_sub_f32_e32 v202, v97, v153
	s_waitcnt lgkmcnt(3)
	v_mfma_f32_32x32x16_bf16 v[82:97], v[66:69], v[114:117], 0
	v_exp_f32_e32 v144, v144
	v_exp_f32_e32 v156, v188
	s_waitcnt lgkmcnt(2)
	v_mfma_f32_32x32x16_bf16 v[66:81], v[70:73], v[114:117], 0
	v_add_u32_e32 v226, s9, v173
	ds_read_b128 v[216:219], v226 offset:16384
	ds_read_b128 v[220:223], v226 offset:24576
	v_exp_f32_e32 v157, v189
	v_exp_f32_e32 v184, v190
	s_waitcnt lgkmcnt(3)
	v_mfma_f32_32x32x16_bf16 v[82:97], v[204:207], v[118:121], v[82:97]
	v_exp_f32_e32 v185, v191
	v_exp_f32_e32 v192, v192
	s_waitcnt lgkmcnt(2)
	v_mfma_f32_32x32x16_bf16 v[66:81], v[208:211], v[118:121], v[66:81]
	v_add_u32_e32 v226, s9, v174
	ds_read_b128 v[204:207], v226 offset:16384
	ds_read_b128 v[208:211], v226 offset:24576
	v_exp_f32_e32 v193, v193
	v_exp_f32_e32 v194, v194
	s_waitcnt lgkmcnt(3)
	v_mfma_f32_32x32x16_bf16 v[82:97], v[216:219], v[126:129], v[82:97]
	v_exp_f32_e32 v195, v195
	v_add_f32_e32 v203, 0, v240
	v_add_f32_e32 v203, v241, v203
	s_waitcnt lgkmcnt(2)
	v_mfma_f32_32x32x16_bf16 v[66:81], v[220:223], v[126:129], v[66:81]
	v_add_u32_e32 v226, s9, v175
	ds_read_b128 v[216:219], v226 offset:16384
	ds_read_b128 v[220:223], v226 offset:24576
	v_exp_f32_e32 v196, v196
	v_add_f32_e32 v203, v242, v203
	v_add_f32_e32 v203, v243, v203
	s_waitcnt lgkmcnt(3)
	v_mfma_f32_32x32x16_bf16 v[82:97], v[204:207], v[122:125], v[82:97]
	v_exp_f32_e32 v197, v197
	v_add_f32_e32 v203, v244, v203
	v_add_f32_e32 v203, v245, v203
	s_waitcnt lgkmcnt(2)
	v_mfma_f32_32x32x16_bf16 v[66:81], v[208:211], v[122:125], v[66:81]
	v_add_u32_e32 v226, s9, v176
	ds_read_b128 v[204:207], v226 offset:16384
	ds_read_b128 v[208:211], v226 offset:24576
	v_exp_f32_e32 v198, v198
	v_add_f32_e32 v203, v246, v203
	v_add_f32_e32 v203, v247, v203
	s_waitcnt lgkmcnt(3)
	v_mfma_f32_32x32x16_bf16 v[82:97], v[216:219], v[110:113], v[82:97]
	v_exp_f32_e32 v199, v199
	v_add_f32_e32 v203, v248, v203
	v_add_f32_e32 v203, v249, v203
	s_waitcnt lgkmcnt(2)
	v_mfma_f32_32x32x16_bf16 v[66:81], v[220:223], v[110:113], v[66:81]
	v_add_u32_e32 v226, s9, v177
	ds_read_b128 v[216:219], v226 offset:16384
	ds_read_b128 v[220:223], v226 offset:24576
	v_exp_f32_e32 v200, v200
	v_add_f32_e32 v203, v250, v203
	v_add_f32_e32 v203, v251, v203
	s_waitcnt lgkmcnt(3)
	v_mfma_f32_32x32x16_bf16 v[82:97], v[204:207], v[106:109], v[82:97]
	v_exp_f32_e32 v201, v201
	v_add_f32_e32 v203, v252, v203
	v_add_f32_e32 v203, v253, v203
	s_waitcnt lgkmcnt(2)
	v_mfma_f32_32x32x16_bf16 v[66:81], v[208:211], v[106:109], v[66:81]
	v_add_u32_e32 v226, s9, v178
	ds_read_b128 v[204:207], v226 offset:16384
	ds_read_b128 v[208:211], v226 offset:24576
	v_exp_f32_e32 v202, v202
	v_add_f32_e32 v203, v254, v203
	v_add_f32_e32 v203, v255, v203
	s_waitcnt lgkmcnt(3)
	v_mfma_f32_32x32x16_bf16 v[82:97], v[216:219], v[102:105], v[82:97]
	v_add_f32_e32 v203, v144, v203
	v_add_f32_e32 v203, v156, v203
	v_cvt_pk_bf16_f32 v130, v240, v241
	s_waitcnt lgkmcnt(2)
	v_mfma_f32_32x32x16_bf16 v[66:81], v[220:223], v[102:105], v[66:81]
	v_add_u32_e32 v226, s9, v179
	ds_read_b128 v[216:219], v226 offset:32768
	ds_read_b128 v[220:223], v226 offset:36864
	ds_read_b128 v[228:231], v163
	v_add_f32_e32 v203, v157, v203
	v_add_f32_e32 v203, v184, v203
	v_cvt_pk_bf16_f32 v131, v242, v243
	s_waitcnt lgkmcnt(4)
	v_mfma_f32_32x32x16_bf16 v[82:97], v[204:207], v[98:101], v[82:97]
	v_add_f32_e32 v203, v185, v203
	v_add_f32_e32 v203, v192, v203
	v_cvt_pk_bf16_f32 v132, v244, v245
	s_waitcnt lgkmcnt(3)
	v_mfma_f32_32x32x16_bf16 v[66:81], v[208:211], v[98:101], v[66:81]
	v_add_u32_e32 v226, s9, v180
	ds_read_b128 v[204:207], v226 offset:32768
	ds_read_b128 v[208:211], v226 offset:36864
	ds_read_b128 v[212:215], v163 offset:1024
	v_add_f32_e32 v203, v193, v203
	v_add_f32_e32 v203, v194, v203
	v_cvt_pk_bf16_f32 v133, v246, v247
	s_waitcnt lgkmcnt(3)
	v_mfma_f32_32x32x16_bf16 v[82:97], v[216:219], v[228:231], v[82:97]
	v_add_f32_e32 v203, v195, v203
	v_add_f32_e32 v203, v196, v203
	v_cvt_pk_bf16_f32 v186, v248, v249
	v_mfma_f32_32x32x16_bf16 v[66:81], v[220:223], v[228:231], v[66:81]
	v_add_u32_e32 v226, s9, v181
	ds_read_b128 v[216:219], v226 offset:32768
	ds_read_b128 v[220:223], v226 offset:36864
	ds_read_b128 v[228:231], v163 offset:2048
	v_add_f32_e32 v203, v197, v203
	v_add_f32_e32 v203, v198, v203
	v_cvt_pk_bf16_f32 v187, v250, v251
	s_waitcnt lgkmcnt(3)
	v_mfma_f32_32x32x16_bf16 v[82:97], v[204:207], v[212:215], v[82:97]
	v_add_f32_e32 v203, v199, v203
	v_add_f32_e32 v203, v200, v203
	v_cvt_pk_bf16_f32 v188, v252, v253
	v_mfma_f32_32x32x16_bf16 v[66:81], v[208:211], v[212:215], v[66:81]
	v_add_u32_e32 v226, s9, v182
	ds_read_b128 v[204:207], v226 offset:32768
	ds_read_b128 v[208:211], v226 offset:36864
	ds_read_b128 v[212:215], v163 offset:3072
	v_add_f32_e32 v203, v201, v203
	v_add_f32_e32 v154, v202, v203
	v_cvt_pk_bf16_f32 v189, v254, v255
	s_waitcnt lgkmcnt(3)
; DI void a_finishSM(f32x16& p0, f32x16& p1, float alpha, float& l_reg, bf16x8& pa0, bf16x8& pa1, bf16x8& pa2, bf16x8& pa3) {
;     ...
;   l_reg = l_reg * alpha + ps;
; DI void pv_sm(f32x16* o, int vb, bf16x8 pa0, bf16x8 pa1, bf16x8 pa2, bf16x8 pa3, f32x16& p0, f32x16& p1, float& m_reg, float& mn, float& alpha) {
;   PV_BLOCK(0)
;   float pm0 = p0[0];
; #pragma unroll
;   for (int r = 1; r < 16; ++r) pm0 = fmaxf(pm0, p0[r]);
;   PV_BLOCK(1)
;   float pmax = pm0;
; #pragma unroll
;   for (int r = 0; r < 16; ++r) pmax = fmaxf(pmax, p1[r]);
;   { auto rr = __builtin_amdgcn_permlane32_swap(__float_as_uint(pmax), __float_as_uint(pmax), false, false);
;     pmax = fmaxf(__uint_as_float(rr[0]), __uint_as_float(rr[1])); }
;   const bool keep = __all(pmax - m_reg <= ATH);
;   mn = keep ? m_reg : fmaxf(m_reg, pmax);
;   alpha = __builtin_amdgcn_exp2f(m_reg - mn);
;   m_reg = mn;
;   PV_BLOCK(2)
; #pragma unroll
;   for (int r = 0; r < 16; ++r) { p0[r] = p0[r] - mn; p1[r] = p1[r] - mn; }
;   PV_BLOCK(3)
; #pragma unroll
;   for (int r = 0; r < 16; ++r) p0[r] = __builtin_amdgcn_exp2f(p0[r]);
; }
	v_mfma_f32_32x32x16_bf16 v[82:97], v[216:219], v[228:231], v[82:97]
	v_mov_b32_e32 v155, v154
	v_cvt_pk_bf16_f32 v190, v144, v156
	v_cvt_pk_bf16_f32 v191, v157, v184
	v_permlane32_swap_b32_e32 v130, v132
	v_mfma_f32_32x32x16_bf16 v[66:81], v[220:223], v[228:231], v[66:81]
	v_add_u32_e32 v232, s7, v171
	ds_read_b64_tr_b16 v[216:217], v232 offset:2048
	ds_read_b64_tr_b16 v[218:219], v232 offset:4096
	ds_read_b64_tr_b16 v[220:221], v232 offset:6144
	ds_read_b64_tr_b16 v[222:223], v232 offset:8192
	ds_read_b64_tr_b16 v[224:225], v232 offset:10240
	ds_read_b64_tr_b16 v[226:227], v232 offset:12288
	ds_read_b64_tr_b16 v[228:229], v232 offset:14336
	v_cvt_pk_bf16_f32 v192, v185, v192
	v_cvt_pk_bf16_f32 v193, v193, v194
	v_permlane32_swap_b32_e32 v154, v155
	v_permlane32_swap_b32_e32 v131, v133
	s_waitcnt lgkmcnt(7)
	v_mfma_f32_32x32x16_bf16 v[82:97], v[204:207], v[212:215], v[82:97]
	v_cvt_pk_bf16_f32 v194, v195, v196
	v_cvt_pk_bf16_f32 v195, v197, v198
	v_permlane32_swap_b32_e32 v186, v188
	v_mfma_f32_32x32x16_bf16 v[66:81], v[208:211], v[212:215], v[66:81]
	ds_read_b64_tr_b16 v[214:215], v232 offset:0
	v_cvt_pk_bf16_f32 v196, v199, v200
	v_cvt_pk_bf16_f32 v197, v201, v202
	v_permlane32_swap_b32_e32 v187, v189
	s_nop 0
	v_permlane32_swap_b32_e32 v190, v192
	v_permlane32_swap_b32_e32 v191, v193
	v_permlane32_swap_b32_e32 v194, v196
	v_permlane32_swap_b32_e32 v195, v197
	v_add_co_u32_e32 v156, vcc, s59, v146
	s_nop 1
	v_addc_co_u32_e32 v157, vcc, 0, v147, vcc
	v_add_co_u32_e32 v146, vcc, s60, v146
	s_nop 1
	v_addc_co_u32_e32 v147, vcc, 0, v147, vcc
	global_load_dwordx4 v[198:201], v[156:157], off offset:256
	global_load_dwordx4 v[202:205], v[156:157], off
	global_load_dwordx4 v[206:209], v[146:147], off offset:256
	global_load_dwordx4 v[210:213], v[146:147], off
	v_add_co_u32_e32 v146, vcc, s61, v148
	s_nop 1
	v_addc_co_u32_e32 v147, vcc, 0, v149, vcc
	global_load_dwordx4 v[146:149], v[146:147], off
	v_lshl_add_u64 v[140:141], v[140:141], 0, s[22:23]
	v_lshl_add_u64 v[142:143], v[142:143], 0, s[24:25]
	v_add_u32_e32 v156, s7, v171
	s_waitcnt lgkmcnt(0)
	s_nop 0
	v_mfma_f32_32x32x16_bf16 v[2:17], v[130:133], v[214:217], v[2:17]
	ds_read_b64_tr_b16 v[214:215], v156 offset:0x200
	ds_read_b64_tr_b16 v[216:217], v156 offset:0xa00
	v_max_f32_e32 v144, v83, v83
	v_max_f32_e32 v157, v82, v82
	v_max_f32_e32 v144, v157, v144
	v_max3_f32 v144, v144, v84, v85
	v_max3_f32 v144, v144, v86, v87
	v_mfma_f32_32x32x16_bf16 v[2:17], v[186:189], v[218:221], v[2:17]
	ds_read_b64_tr_b16 v[218:219], v156 offset:0x1200
	ds_read_b64_tr_b16 v[220:221], v156 offset:0x1a00
	v_max3_f32 v144, v144, v88, v89
	v_max3_f32 v144, v144, v90, v91
	v_max3_f32 v144, v144, v92, v93
	v_max3_f32 v144, v144, v94, v95
	v_max3_f32 v144, v144, v96, v97
	v_add_f32_e32 v239, v150, v151
	v_fmac_f32_e32 v239, v183, v162
	v_add_f32_e32 v162, v154, v155
	v_fmac_f32_e32 v162, v239, v152
	v_mfma_f32_32x32x16_bf16 v[2:17], v[190:193], v[222:225], v[2:17]
	ds_read_b64_tr_b16 v[222:223], v156 offset:0x2200
	ds_read_b64_tr_b16 v[224:225], v156 offset:0x2a00
	ds_read_b64_tr_b16 v[230:231], v156 offset:0x3200
	ds_read_b64_tr_b16 v[232:233], v156 offset:0x3a00
	v_mfma_f32_32x32x16_bf16 v[2:17], v[194:197], v[226:229], v[2:17]
	s_waitcnt lgkmcnt(0)
	v_mfma_f32_32x32x16_bf16 v[50:65], v[130:133], v[214:217], v[50:65]
	v_max3_f32 v144, v144, v66, v67
	v_max3_f32 v144, v144, v68, v69
	v_max3_f32 v144, v144, v70, v71
	v_max3_f32 v144, v144, v72, v73
	v_max3_f32 v144, v144, v74, v75
	v_max3_f32 v144, v144, v76, v77
	v_max3_f32 v144, v144, v78, v79
	v_mfma_f32_32x32x16_bf16 v[50:65], v[186:189], v[218:221], v[50:65]
	v_max3_f32 v144, v144, v80, v81
	v_mov_b32_e32 v157, v144
	s_nop 1
	v_permlane32_swap_b32_e32 v144, v157
	v_max_f32_e32 v157, v157, v157
	v_max_f32_e32 v144, v144, v144
	v_max_f32_e32 v144, v144, v157
	v_mfma_f32_32x32x16_bf16 v[50:65], v[190:193], v[222:225], v[50:65]
	ds_read_b64_tr_b16 v[214:215], v156 offset:0x400
	v_sub_f32_e32 v157, v144, v153
	ds_read_b64_tr_b16 v[216:217], v156 offset:0xc00
	v_cmp_ge_f32_e32 vcc, s54, v157
	ds_read_b64_tr_b16 v[218:219], v156 offset:0x1400
	s_cmp_eq_u64 vcc, exec
	v_max_f32_e32 v157, v153, v153
	ds_read_b64_tr_b16 v[220:221], v156 offset:0x1c00
	ds_read_b64_tr_b16 v[222:223], v156 offset:0x2400
	ds_read_b64_tr_b16 v[224:225], v156 offset:0x2c00
	ds_read_b64_tr_b16 v[226:227], v156 offset:0x3400
	ds_read_b64_tr_b16 v[228:229], v156 offset:0x3c00
	v_mfma_f32_32x32x16_bf16 v[50:65], v[194:197], v[230:233], v[50:65]
	v_max_f32_e32 v144, v157, v144
	s_cselect_b64 vcc, -1, 0
	v_cndmask_b32_e32 v144, v144, v153, vcc
	v_sub_f32_e32 v153, v153, v144
	v_exp_f32_e32 v184, v153
	s_waitcnt lgkmcnt(0)
	v_mfma_f32_32x32x16_bf16 v[34:49], v[130:133], v[214:217], v[34:49]
	ds_read_b64_tr_b16 v[214:215], v156 offset:0x600
	ds_read_b64_tr_b16 v[216:217], v156 offset:0xe00
	v_sub_f32_e32 v82, v82, v144
	v_sub_f32_e32 v83, v83, v144
	v_sub_f32_e32 v84, v84, v144
	v_sub_f32_e32 v85, v85, v144
	v_mfma_f32_32x32x16_bf16 v[34:49], v[186:189], v[218:221], v[34:49]
	ds_read_b64_tr_b16 v[218:219], v156 offset:0x1600
	ds_read_b64_tr_b16 v[220:221], v156 offset:0x1e00
	v_sub_f32_e32 v86, v86, v144
	v_sub_f32_e32 v87, v87, v144
	v_exp_f32_e32 v240, v82
	v_exp_f32_e32 v241, v83
	v_mfma_f32_32x32x16_bf16 v[34:49], v[190:193], v[222:225], v[34:49]
	ds_read_b64_tr_b16 v[222:223], v156 offset:0x2600
	ds_read_b64_tr_b16 v[224:225], v156 offset:0x2e00
	ds_read_b64_tr_b16 v[230:231], v156 offset:0x3600
	ds_read_b64_tr_b16 v[232:233], v156 offset:0x3e00
	v_mfma_f32_32x32x16_bf16 v[34:49], v[194:197], v[226:229], v[34:49]
	v_sub_f32_e32 v88, v88, v144
	v_sub_f32_e32 v89, v89, v144
	v_exp_f32_e32 v242, v84
	v_exp_f32_e32 v243, v85
	s_waitcnt lgkmcnt(0)
	v_sub_f32_e32 v90, v90, v144
	v_sub_f32_e32 v91, v91, v144
	v_exp_f32_e32 v244, v86
	v_exp_f32_e32 v245, v87
	v_mfma_f32_32x32x16_bf16 v[18:33], v[130:133], v[214:217], v[18:33]
	v_sub_f32_e32 v92, v92, v144
	v_sub_f32_e32 v93, v93, v144
	v_exp_f32_e32 v246, v88
	v_exp_f32_e32 v247, v89
	s_add_i32 s9, s8, 0
	v_add_u32_e32 v130, s9, v164
	s_waitcnt vmcnt(0)
	s_waitcnt vmcnt(4)
	ds_write_b128 v130, v[198:201]
	v_add_u32_e32 v130, s9, v165
	s_waitcnt vmcnt(2)
	ds_write_b128 v130, v[206:209]
	v_add_u32_e32 v130, s9, v167
	v_mfma_f32_32x32x16_bf16 v[18:33], v[186:189], v[218:221], v[18:33]
	ds_write_b128 v130, v[202:205] offset:16384
	v_add_u32_e32 v130, s9, v168
	s_waitcnt vmcnt(1)
	ds_write_b128 v130, v[210:213] offset:16384
	v_add_u32_e32 v130, s9, v169
	v_cmp_gt_f32_e32 vcc, 1.0, v184
	s_waitcnt vmcnt(0)
	ds_write_b128 v130, v[146:149] offset:32768
	v_sub_f32_e32 v94, v94, v144
	v_sub_f32_e32 v95, v95, v144
	v_exp_f32_e32 v248, v90
	v_exp_f32_e32 v249, v91
	v_mfma_f32_32x32x16_bf16 v[18:33], v[190:193], v[222:225], v[18:33]
	v_sub_f32_e32 v96, v96, v144
	v_sub_f32_e32 v97, v97, v144
	v_exp_f32_e32 v250, v92
	v_exp_f32_e32 v251, v93
	v_mfma_f32_32x32x16_bf16 v[18:33], v[194:197], v[230:233], v[18:33]
	v_exp_f32_e32 v252, v94
	v_exp_f32_e32 v253, v95
	v_exp_f32_e32 v254, v96
	v_exp_f32_e32 v255, v97
	s_cbranch_vccz .LBB0_673
; #define SBAR() __builtin_amdgcn_sched_barrier(0)
; #define SLOAD(k0) do { vs0 = *(const bf16x8*)(&Vh[(long)((k0) + sr) * LDK + sc]); vs1 = *(const bf16x8*)(&Vh[(long)((k0) + 32 + sr) * LDK + sc]); \
;     ks0 = *(const bf16x8*)(&Kh[(long)((k0) + sr) * LDK + sc]); ks1 = *(const bf16x8*)(&Kh[(long)((k0) + 32 + sr) * LDK + sc]); \
;     ps0 = *(const bf16x8*)(&Ph[(long)((k0) + pr) * LDP + pc]); } while (0)
; #define SWRITE(st) do { char* b_ = lds + (st); *(bf16x8*)(b_ + vst0) = vs0; *(bf16x8*)(b_ + vst1) = vs1; const int kc = sc * 2; \
;     *(bf16x8*)(b_ + A_KO + KSWZ(sr, kc)) = ks0; *(bf16x8*)(b_ + A_KO + KSWZ(32 + sr, kc)) = ks1; \
;     *(bf16x8*)(b_ + A_PO + PSWZ(pr, pc * 2)) = ps0; } while (0)
; #define SWAIT() asm volatile("s_waitcnt vmcnt(0)" ::: "memory")
; #define RESC(a) do { if (__any((a) < 1.f)) { if (hi == 0) al_l[r32] = (a); asm volatile("s_waitcnt lgkmcnt(0)" ::: "memory"); \
;     _Pragma("unroll") for (int d = 0; d < 4; ++d) _Pragma("unroll") for (int r = 0; r < 16; ++r) o[d][r] *= al_l[crow(r, hi)]; } } while (0)
; DI void attn_unit(const bf16_t* __restrict__ Qb, const bf16_t* __restrict__ Kh, const bf16_t* __restrict__ Vh, const bf16_t* __restrict__ Ph,
;                   bf16_t* __restrict__ Ob, int seq, float* __restrict__ lse_out, char* lds) {
;     ...
;     RESC(alB); __syncthreads();
;     { const int t_ = sV; sV = sK; sK = sW; sW = t_; }
;     SBAR(); a_qkt(pA0, pA1, lds + sK + A_KO, lds + sK + A_PO, qr, QP, r32, hi);
;     a_finishSM(pB0, pB1, alB, l_reg, pa0, pa1, pa2, pa3); SBAR();
;     SLOAD((j + 2) * 64); SBAR();
;     pv_sm(o, vb0 + sV, pa0, pa1, pa2, pa3, pA0, pA1, m_reg, mnA, alA);
;     SWAIT(); SWRITE(sW);
;     RESC(alA); __syncthreads();
;     { const int t_ = sV; sV = sK; sK = sW; sW = t_; }
	s_and_saveexec_b64 s[4:5], s[2:3]
	ds_write_b32 v161, v184 offset:128
	s_or_b64 exec, exec, s[4:5]
	s_waitcnt lgkmcnt(0)
	v_add_u32_e32 v153, v137, v134
	ds_read_b128 v[130:133], v153 offset:224
	ds_read_b128 v[146:149], v153 offset:192
	ds_read_b128 v[186:189], v153 offset:160
	ds_read_b128 v[190:193], v153 offset:128
	s_waitcnt lgkmcnt(3)
	v_pk_mul_f32 v[14:15], v[14:15], v[130:131]
	s_waitcnt lgkmcnt(2)
	v_pk_mul_f32 v[10:11], v[10:11], v[146:147]
	s_waitcnt lgkmcnt(1)
	v_pk_mul_f32 v[6:7], v[6:7], v[186:187]
	v_pk_mul_f32 v[16:17], v[16:17], v[132:133]
	v_pk_mul_f32 v[12:13], v[12:13], v[148:149]
	v_pk_mul_f32 v[8:9], v[8:9], v[188:189]
	s_waitcnt lgkmcnt(0)
	v_pk_mul_f32 v[4:5], v[4:5], v[192:193]
	v_pk_mul_f32 v[2:3], v[2:3], v[190:191]
	v_pk_mul_f32 v[62:63], v[62:63], v[130:131]
	v_pk_mul_f32 v[58:59], v[58:59], v[146:147]
	v_pk_mul_f32 v[54:55], v[54:55], v[186:187]
	v_pk_mul_f32 v[64:65], v[64:65], v[132:133]
	v_pk_mul_f32 v[60:61], v[60:61], v[148:149]
	v_pk_mul_f32 v[56:57], v[56:57], v[188:189]
	v_pk_mul_f32 v[52:53], v[52:53], v[192:193]
	v_pk_mul_f32 v[50:51], v[50:51], v[190:191]
	v_pk_mul_f32 v[46:47], v[46:47], v[130:131]
	v_pk_mul_f32 v[42:43], v[42:43], v[146:147]
	v_pk_mul_f32 v[38:39], v[38:39], v[186:187]
	v_pk_mul_f32 v[48:49], v[48:49], v[132:133]
	v_pk_mul_f32 v[44:45], v[44:45], v[148:149]
	v_pk_mul_f32 v[40:41], v[40:41], v[188:189]
	v_pk_mul_f32 v[36:37], v[36:37], v[192:193]
	v_pk_mul_f32 v[34:35], v[34:35], v[190:191]
	v_pk_mul_f32 v[30:31], v[30:31], v[130:131]
	v_pk_mul_f32 v[26:27], v[26:27], v[146:147]
	v_pk_mul_f32 v[22:23], v[22:23], v[186:187]
	v_pk_mul_f32 v[32:33], v[32:33], v[132:133]
	v_pk_mul_f32 v[28:29], v[28:29], v[148:149]
	v_pk_mul_f32 v[24:25], v[24:25], v[188:189]
	v_pk_mul_f32 v[20:21], v[20:21], v[192:193]
	v_pk_mul_f32 v[18:19], v[18:19], v[190:191]
.LBB0_673:
	v_pk_add_f32 v[130:131], v[66:67], v[144:145] op_sel_hi:[1,0] neg_lo:[0,1] neg_hi:[0,1]
	v_pk_add_f32 v[146:147], v[68:69], v[144:145] op_sel_hi:[1,0] neg_lo:[0,1] neg_hi:[0,1]
	v_pk_add_f32 v[132:133], v[70:71], v[144:145] op_sel_hi:[1,0] neg_lo:[0,1] neg_hi:[0,1]
	v_pk_add_f32 v[148:149], v[72:73], v[144:145] op_sel_hi:[1,0] neg_lo:[0,1] neg_hi:[0,1]
	v_pk_add_f32 v[150:151], v[74:75], v[144:145] op_sel_hi:[1,0] neg_lo:[0,1] neg_hi:[0,1]
	v_pk_add_f32 v[154:155], v[76:77], v[144:145] op_sel_hi:[1,0] neg_lo:[0,1] neg_hi:[0,1]
	v_pk_add_f32 v[152:153], v[78:79], v[144:145] op_sel_hi:[1,0] neg_lo:[0,1] neg_hi:[0,1]
	v_pk_add_f32 v[156:157], v[80:81], v[144:145] op_sel_hi:[1,0] neg_lo:[0,1] neg_hi:[0,1]
	s_add_i32 s66, s66, 2
	s_cmp_ge_u32 s66, s53
	s_cbranch_scc1 .Lattn_exit_bar
	s_mov_b32 s4, s6
	s_mov_b32 s6, s7
	s_mov_b32 s7, s8
	v_mov_b32_e32 v183, v184
	s_waitcnt lgkmcnt(0)
	s_barrier
	s_branch .LBB0_665
